# new: idle wave 2 prefetches 16 KB of the next phase's code into L2 while waiting in each grid barrier (after the acquiring invalidate), on top of v129
# baseline (speedup 1.0000x reference)
.LBB0_74:
	s_or_b64 exec, exec, s[2:3]
	v_readfirstlane_b32 s4, v0
	s_lshr_b32 s4, s4, 6
	s_cmp_lg_u32 s4, 2
	s_cbranch_scc1 .Lmy_nopf_0
	s_sleep 60
	s_getpc_b64 s[4:5]
	v_and_b32_e32 v2, 63, v0
	v_lshlrev_b32_e32 v2, 4, v2
	global_load_dwordx4 v[4:7], v2, s[4:5]
	global_load_dwordx4 v[4:7], v2, s[4:5] offset:1024
	global_load_dwordx4 v[4:7], v2, s[4:5] offset:2048
	global_load_dwordx4 v[4:7], v2, s[4:5] offset:3072
	s_add_u32 s4, s4, 0x1000
	s_addc_u32 s5, s5, 0
	global_load_dwordx4 v[4:7], v2, s[4:5]
	global_load_dwordx4 v[4:7], v2, s[4:5] offset:1024
	global_load_dwordx4 v[4:7], v2, s[4:5] offset:2048
	global_load_dwordx4 v[4:7], v2, s[4:5] offset:3072
	s_add_u32 s4, s4, 0x1000
	s_addc_u32 s5, s5, 0
	global_load_dwordx4 v[4:7], v2, s[4:5]
	global_load_dwordx4 v[4:7], v2, s[4:5] offset:1024
	global_load_dwordx4 v[4:7], v2, s[4:5] offset:2048
	global_load_dwordx4 v[4:7], v2, s[4:5] offset:3072
	s_add_u32 s4, s4, 0x1000
	s_addc_u32 s5, s5, 0
	global_load_dwordx4 v[4:7], v2, s[4:5]
	global_load_dwordx4 v[4:7], v2, s[4:5] offset:1024
	global_load_dwordx4 v[4:7], v2, s[4:5] offset:2048
	global_load_dwordx4 v[4:7], v2, s[4:5] offset:3072
	s_waitcnt vmcnt(0)
.Lmy_nopf_0:
	s_barrier
.LBB0_75:
	s_add_u32 s16, s58, 0x2c00000
	s_addc_u32 s79, s59, 0
	s_cmp_lt_i32 s60, 2
	s_cselect_b64 s[2:3], -1, 0
	s_cmp_gt_i32 s61, 1
	s_cselect_b64 s[4:5], -1, 0
	s_and_b64 s[2:3], s[2:3], s[4:5]
	s_andn2_b64 vcc, exec, s[2:3]
	v_writelane_b32 v254, s34, 21
	s_cbranch_vccnz .LBB0_115
	s_lshl_b32 s2, s33, 3
	s_abs_i32 s3, s2
	v_cvt_f32_u32_e32 v2, s3
	s_sub_i32 s4, 0, s3
	s_ashr_i32 s2, s2, 31
	s_mov_b32 s15, 0
	v_rcp_iflag_f32_e32 v2, v2
	s_nop 0
	v_mul_f32_e32 v2, 0x4f7ffffe, v2
	v_cvt_u32_f32_e32 v2, v2
	s_nop 0
	v_readfirstlane_b32 s5, v2
	s_mul_i32 s4, s4, s5
	s_mul_hi_u32 s4, s5, s4
	s_add_i32 s5, s5, s4
	s_lshr_b32 s4, s5, 18
	s_mul_i32 s5, s4, s3
	s_sub_i32 s5, 0x4000, s5
	s_add_i32 s6, s4, 1
	s_sub_i32 s7, s5, s3
	s_cmp_ge_u32 s5, s3
	s_cselect_b32 s4, s6, s4
	s_cselect_b32 s5, s7, s5
	s_add_i32 s6, s4, 1
	s_cmp_ge_u32 s5, s3
	s_cselect_b32 s3, s6, s4
	s_xor_b32 s3, s3, s2
	s_sub_i32 s14, s3, s2
	s_cmp_lt_i32 s14, 1
	s_cbranch_scc1 .LBB0_79
	v_readlane_b32 s2, v254, 18
	v_readlane_b32 s3, v254, 19
	s_lshl_b32 s2, s2, 3
	v_readlane_b32 s3, v254, 20
	s_add_i32 s2, s2, s3
	s_mul_i32 s2, s14, s2
	s_ashr_i32 s3, s2, 31
	s_lshr_b32 s4, s3, 20
	s_add_i32 s4, s2, s4
	s_ashr_i32 s4, s4, 12
	s_mulk_i32 s4, 0x2400
	s_ashr_i32 s5, s4, 31
	s_lshl_b64 s[4:5], s[4:5], 2
	s_add_u32 s0, s0, s4
	s_addc_u32 s1, s1, s5
	s_add_u32 s4, s0, 0x1000
	s_waitcnt vmcnt(8)
	v_lshlrev_b32_e32 v50, 5, v1
	s_addc_u32 s5, s1, 0
	v_or_b32_e32 v2, 0x800, v50
	global_load_dwordx4 v[18:21], v50, s[4:5]
	global_load_dwordx4 v[22:25], v50, s[4:5] offset:16
	global_load_dwordx4 v[26:29], v2, s[4:5]
	global_load_dwordx4 v[30:33], v2, s[4:5] offset:16
	v_readlane_b32 s80, v254, 2
	v_readlane_b32 s88, v254, 10
	v_readlane_b32 s89, v254, 11
	v_readlane_b32 s90, v254, 12
	v_readlane_b32 s91, v254, 13
	v_readlane_b32 s92, v254, 14
	v_readlane_b32 s93, v254, 15
	v_readlane_b32 s94, v254, 16
	v_readlane_b32 s95, v254, 17
	s_mov_b64 s[20:21], s[88:89]
	global_load_dwordx4 v[34:37], v50, s[20:21]
	global_load_dwordx4 v[38:41], v50, s[20:21] offset:16
	global_load_dwordx4 v[42:45], v50, s[20:21] offset:2048
	global_load_dwordx4 v[46:49], v50, s[20:21] offset:2064
	global_load_dwordx4 v[2:5], v50, s[0:1] offset:16
	global_load_dwordx4 v[6:9], v50, s[0:1]
	global_load_dwordx4 v[10:13], v50, s[0:1] offset:2064
	global_load_dwordx4 v[14:17], v50, s[0:1] offset:2048
	s_waitcnt vmcnt(17)
	v_mbcnt_lo_u32_b32 v52, -1, 0
	v_mbcnt_hi_u32_b32 v52, -1, v52
	v_and_b32_e32 v54, 64, v52
	v_xor_b32_e32 v55, 1, v52
	v_add_u32_e32 v54, 64, v54
	s_waitcnt vmcnt(16)
	v_lshlrev_b32_e32 v53, 4, v1
	v_xor_b32_e32 v56, 2, v52
	v_cmp_lt_i32_e32 vcc, v55, v54
	v_xor_b32_e32 v57, 4, v52
	v_lshl_or_b32 v70, s2, 11, v53
	v_cndmask_b32_e32 v53, v52, v55, vcc
	v_cmp_lt_i32_e32 vcc, v56, v54
	v_readlane_b32 s81, v254, 3
	v_xor_b32_e32 v58, 8, v52
	v_cndmask_b32_e32 v55, v52, v56, vcc
	v_cmp_lt_i32_e32 vcc, v57, v54
	s_mov_b64 s[12:13], s[80:81]
	v_xor_b32_e32 v59, 16, v52
	v_cndmask_b32_e32 v56, v52, v57, vcc
	v_cmp_lt_i32_e32 vcc, v58, v54
	s_and_b32 s17, s79, 0xffff
	s_lshl_b64 s[2:3], s[2:3], 12
	v_xor_b32_e32 v60, 32, v52
	v_cndmask_b32_e32 v57, v52, v58, vcc
	v_cmp_lt_i32_e32 vcc, v59, v54
	s_add_u32 s2, s12, s2
	v_mov_b32_e32 v51, 0
	v_cndmask_b32_e32 v58, v52, v59, vcc
	v_cmp_lt_i32_e32 vcc, v60, v54
	s_addc_u32 s3, s13, s3
	s_mov_b64 s[0:1], 0x1000
	v_cndmask_b32_e32 v52, v52, v60, vcc
	v_lshl_add_u64 v[50:51], s[2:3], 0, v[50:51]
	s_mov_b32 s19, 0x20000
	s_brev_b32 s18, 64
	v_mov_b32_e32 v68, 0x358637bd
	s_mov_b32 s20, 0xf800000
	v_mov_b32_e32 v69, 0x260
	v_lshlrev_b32_e32 v71, 2, v53
	v_lshlrev_b32_e32 v72, 2, v55
	v_lshlrev_b32_e32 v73, 2, v56
	v_lshlrev_b32_e32 v74, 2, v57
	v_lshlrev_b32_e32 v75, 2, v58
	v_lshlrev_b32_e32 v76, 2, v52
	v_lshl_add_u64 v[50:51], v[50:51], 0, s[0:1]
	s_mov_b64 s[6:7], 0x2000
	v_readlane_b32 s82, v254, 4
	v_readlane_b32 s83, v254, 5
	v_readlane_b32 s84, v254, 6
	v_readlane_b32 s85, v254, 7
	v_readlane_b32 s86, v254, 8
	v_readlane_b32 s87, v254, 9
	s_mov_b64 s[22:23], s[90:91]
	s_mov_b64 s[24:25], s[92:93]
	s_mov_b64 s[26:27], s[94:95]
	s_waitcnt vmcnt(11)
	v_pk_add_f32 v[20:21], v[20:21], 1.0 op_sel_hi:[1,0]
	v_pk_add_f32 v[18:19], v[18:19], 1.0 op_sel_hi:[1,0]
	s_waitcnt vmcnt(10)
	v_pk_add_f32 v[24:25], v[24:25], 1.0 op_sel_hi:[1,0]
	v_pk_add_f32 v[22:23], v[22:23], 1.0 op_sel_hi:[1,0]
	s_waitcnt vmcnt(9)
	v_pk_add_f32 v[28:29], v[28:29], 1.0 op_sel_hi:[1,0]
	v_pk_add_f32 v[26:27], v[26:27], 1.0 op_sel_hi:[1,0]
	s_waitcnt vmcnt(8)
	v_pk_add_f32 v[32:33], v[32:33], 1.0 op_sel_hi:[1,0]
	v_pk_add_f32 v[30:31], v[30:31], 1.0 op_sel_hi:[1,0]
	s_waitcnt vmcnt(7)
	v_pk_mul_f32 v[52:53], v[36:37], v[20:21]
	v_pk_mul_f32 v[54:55], v[34:35], v[18:19]
	s_waitcnt vmcnt(6)
	v_pk_mul_f32 v[56:57], v[40:41], v[24:25]
	v_pk_mul_f32 v[58:59], v[38:39], v[22:23]
	s_waitcnt vmcnt(5)
	v_pk_mul_f32 v[60:61], v[44:45], v[28:29]
	v_pk_mul_f32 v[62:63], v[42:43], v[26:27]
	s_waitcnt vmcnt(4)
	v_pk_mul_f32 v[64:65], v[48:49], v[32:33]
	v_pk_mul_f32 v[66:67], v[46:47], v[30:31]

.LBB0_114:
	s_or_b64 exec, exec, s[0:1]
	v_readfirstlane_b32 s4, v0
	s_lshr_b32 s4, s4, 6
	s_cmp_lg_u32 s4, 2
	s_cbranch_scc1 .Lmy_nopf_1
	s_sleep 60
	s_getpc_b64 s[4:5]
	v_and_b32_e32 v2, 63, v0
	v_lshlrev_b32_e32 v2, 4, v2
	global_load_dwordx4 v[4:7], v2, s[4:5]
	global_load_dwordx4 v[4:7], v2, s[4:5] offset:1024
	global_load_dwordx4 v[4:7], v2, s[4:5] offset:2048
	global_load_dwordx4 v[4:7], v2, s[4:5] offset:3072
	s_add_u32 s4, s4, 0x1000
	s_addc_u32 s5, s5, 0
	global_load_dwordx4 v[4:7], v2, s[4:5]
	global_load_dwordx4 v[4:7], v2, s[4:5] offset:1024
	global_load_dwordx4 v[4:7], v2, s[4:5] offset:2048
	global_load_dwordx4 v[4:7], v2, s[4:5] offset:3072
	s_add_u32 s4, s4, 0x1000
	s_addc_u32 s5, s5, 0
	global_load_dwordx4 v[4:7], v2, s[4:5]
	global_load_dwordx4 v[4:7], v2, s[4:5] offset:1024
	global_load_dwordx4 v[4:7], v2, s[4:5] offset:2048
	global_load_dwordx4 v[4:7], v2, s[4:5] offset:3072
	s_add_u32 s4, s4, 0x1000
	s_addc_u32 s5, s5, 0
	global_load_dwordx4 v[4:7], v2, s[4:5]
	global_load_dwordx4 v[4:7], v2, s[4:5] offset:1024
	global_load_dwordx4 v[4:7], v2, s[4:5] offset:2048
	global_load_dwordx4 v[4:7], v2, s[4:5] offset:3072
	s_waitcnt vmcnt(0)
.Lmy_nopf_1:
	s_barrier
.LBB0_115:
	s_cmp_lt_i32 s60, 3
	s_cselect_b64 s[0:1], -1, 0
	s_cmp_gt_i32 s61, 2
	s_cselect_b64 s[2:3], -1, 0
	s_and_b64 s[0:1], s[0:1], s[2:3]
	s_andn2_b64 vcc, exec, s[0:1]
	s_cbranch_vccnz .LBB0_217
	s_cmpk_gt_i32 s10, 0x57f
	v_readfirstlane_b32 s3, v0
	s_cbranch_scc1 .LBB0_132
	v_lshlrev_b32_e32 v2, 4, v0
	v_and_b32_e32 v3, 32, v0
	v_bitop3_b32 v2, v2, v3, 48 bitop3:0x6c
	v_and_or_b32 v3, v0, 64, v2
	v_lshrrev_b32_e32 v2, 1, v0
	s_waitcnt vmcnt(34)
	v_lshrrev_b32_e32 v5, 5, v0
	v_and_b32_e32 v2, 24, v2
	v_and_b32_e32 v5, 4, v5
	v_bfe_u32 v6, v0, 2, 2
	v_bfe_u32 v4, v0, 2, 4
	v_or3_b32 v5, v5, v6, v2
	v_lshrrev_b32_e32 v6, 3, v0
	v_and_or_b32 v7, v6, 48, v4
	v_and_or_b32 v6, v6, 32, v5
	v_lshl_or_b32 v135, v6, 11, v3
	v_bfe_u32 v6, v0, 3, 25
	s_add_u32 s17, s58, 0x300000
	v_or_b32_e32 v6, 64, v6
	s_movk_i32 s0, 0x70
	s_addc_u32 s19, s59, 0
	v_and_or_b32 v4, v6, s0, v4
	s_movk_i32 s0, 0x60
	s_ashr_i32 s81, s10, 31
	v_and_or_b32 v5, v6, s0, v5
	s_lshr_b32 s0, s81, 29
	s_add_i32 s0, s10, s0
	s_lshr_b32 s6, s3, 6
	s_ashr_i32 s1, s0, 3
	s_and_b32 s0, s0, -8
	s_lshr_b32 s5, s3, 8
	s_lshl_b32 s63, s6, 10
	s_sub_i32 s0, s10, s0
	s_cmp_lt_i32 s0, 0
	s_movk_i32 s82, 0xb1
	s_cselect_b32 s2, s82, 0xb0
	s_mul_i32 s0, s0, s2
	s_add_i32 s0, s0, s1
	s_mul_hi_i32 s1, s0, 0x2e8ba2e9
	s_lshr_b32 s2, s1, 31
	s_ashr_i32 s1, s1, 4
	s_add_i32 s1, s1, s2
	s_lshl_b32 s4, s1, 2
	s_mulk_i32 s1, 0x58
	s_sub_i32 s0, s0, s1
	s_bfe_i32 s1, s0, 0x80000
	s_bfe_u32 s1, s1, 0x2000d
	s_add_i32 s1, s0, s1
	s_bfe_i32 s2, s1, 0x80000
	s_and_b32 s1, s1, 0xfc
	s_sub_i32 s0, s0, s1
	s_sext_i32_i16 s2, s2
	s_sext_i32_i8 s0, s0
	s_lshr_b32 s2, s2, 2
	s_add_i32 s66, s4, s0
	s_ashr_i32 s67, s66, 31
	s_bfe_i64 s[8:9], s[2:3], 0x100000
	s_lshl_b64 s[0:1], s[66:67], 19
	s_lshl_b64 s[8:9], s[8:9], 19
	s_add_u32 s68, s17, s8
	s_addc_u32 s69, s19, s9
	s_add_i32 s67, s63, 0
	v_lshl_or_b32 v134, v7, 11, v3
	v_lshl_or_b32 v136, v4, 11, v3
	v_lshl_or_b32 v137, v5, 11, v3
	s_mov_b64 s[8:9], s[68:69]
	s_add_i32 m0, s67, 0x10000
	v_mov_b32_e32 v3, v135
	v_mov_b32_e32 v4, v137
	global_load_lds_dwordx4 v3, s[8:9]
	s_add_i32 m0, s67, 0x12000
	s_mov_b32 s26, s62
	global_load_lds_dwordx4 v4, s[8:9]
	s_add_u32 s8, s68, 0x40000
	s_addc_u32 s9, s69, 0
	s_add_i32 m0, s67, 0x14000
	s_mov_b64 s[24:25], s[96:97]
	global_load_lds_dwordx4 v3, s[8:9]
	s_add_i32 m0, s67, 0x16000
	s_add_u32 s72, s16, s0
	s_addc_u32 s73, s79, s1
	global_load_lds_dwordx4 v4, s[8:9]
	s_mov_b64 s[0:1], s[72:73]
	v_mov_b32_e32 v3, v134
	s_mov_b32 m0, s67
	s_add_i32 s83, s67, 0x2000
	v_mov_b32_e32 v4, v136
	global_load_lds_dwordx4 v3, s[0:1]
	s_mov_b32 m0, s83
	s_mov_b32 s86, 0
	global_load_lds_dwordx4 v4, s[0:1]
	s_add_u32 s0, s72, 0x40000
	s_addc_u32 s1, s73, 0
	s_add_i32 s84, s67, 0x4000
	s_mov_b32 m0, s84
	s_add_i32 s85, s67, 0x6000
	s_cmp_eq_u32 s5, 1
	global_load_lds_dwordx4 v3, s[0:1]
	s_mov_b32 m0, s85
	s_nop 0
	global_load_lds_dwordx4 v4, s[0:1]
	s_cselect_b64 s[0:1], -1, 0
	s_cmp_lg_u32 s5, 1
	s_cbranch_scc1 .LBB0_119
	s_barrier

.Lmy_nopf_2:
	s_barrier
.LBB0_217:
	s_cmp_lt_i32 s60, 4
	s_cselect_b64 s[0:1], -1, 0
	s_cmp_gt_i32 s61, 3
	s_cselect_b64 s[2:3], -1, 0
	s_and_b64 s[0:1], s[0:1], s[2:3]
	s_andn2_b64 vcc, exec, s[0:1]
	s_cbranch_vccnz .LBB0_318
	s_cmpk_gt_i32 s10, 0xff
	v_readfirstlane_b32 s72, v0
	s_cbranch_scc1 .LBB0_282
	s_ashr_i32 s73, s10, 31
	s_lshr_b32 s0, s73, 29
	s_add_i32 s3, s10, s0
	s_and_b32 s0, s3, -8
	s_sub_i32 s4, s10, s0
	s_cmp_gt_i32 s4, -1
	s_cbranch_scc0 .LBB0_221
	s_lshl_b32 s2, s4, 5
	s_cbranch_execz .LBB0_222
	s_branch .LBB0_223

.Lmy_nopf_3:
	s_barrier
.LBB0_318:
	s_cmp_lt_i32 s60, 5
	s_cselect_b64 s[0:1], -1, 0
	s_cmp_gt_i32 s61, 4
	s_cselect_b64 s[2:3], -1, 0
	s_and_b64 s[0:1], s[0:1], s[2:3]
	s_andn2_b64 vcc, exec, s[0:1]
	s_cbranch_vccnz .LBB0_379
	s_cmpk_gt_i32 s10, 0x2ff
	v_readfirstlane_b32 s3, v0
	s_cbranch_scc1 .LBB0_343
	v_lshlrev_b32_e32 v2, 4, v0
	v_and_b32_e32 v3, 32, v0
	v_bitop3_b32 v2, v2, v3, 48 bitop3:0x6c
	v_and_or_b32 v3, v0, 64, v2
	v_lshrrev_b32_e32 v2, 1, v0
	s_waitcnt vmcnt(0)
	v_lshrrev_b32_e32 v5, 5, v0
	v_and_b32_e32 v2, 24, v2
	v_and_b32_e32 v5, 4, v5
	v_bfe_u32 v6, v0, 2, 2
	v_bfe_u32 v4, v0, 2, 4
	v_or3_b32 v5, v5, v6, v2
	v_lshrrev_b32_e32 v6, 3, v0
	v_and_or_b32 v7, v6, 48, v4
	v_and_or_b32 v6, v6, 32, v5
	v_lshl_or_b32 v135, v6, 11, v3
	v_bfe_u32 v6, v0, 3, 25
	s_add_u32 s17, s58, 0x2400000
	v_or_b32_e32 v6, 64, v6
	s_movk_i32 s0, 0x70
	s_addc_u32 s63, s59, 0
	v_and_or_b32 v4, v6, s0, v4
	s_movk_i32 s0, 0x60
	s_ashr_i32 s82, s10, 31
	v_and_or_b32 v5, v6, s0, v5
	s_lshr_b32 s0, s82, 29
	s_add_i32 s0, s10, s0
	s_lshr_b32 s6, s3, 6
	s_ashr_i32 s1, s0, 3
	s_and_b32 s0, s0, -8
	s_lshr_b32 s5, s3, 8
	s_lshl_b32 s81, s6, 10
	s_sub_i32 s0, s10, s0
	s_cmp_lt_i32 s0, 0
	s_movk_i32 s83, 0x61
	s_cselect_b32 s2, s83, 0x60
	s_mul_i32 s0, s0, s2
	s_add_i32 s0, s0, s1
	s_mul_hi_i32 s1, s0, 0x2aaaaaab
	s_lshr_b32 s2, s1, 31
	s_ashr_i32 s1, s1, 3
	s_add_i32 s1, s1, s2
	s_lshl_b32 s4, s1, 2
	s_mul_i32 s1, s1, 48
	s_sub_i32 s0, s0, s1
	s_bfe_i32 s1, s0, 0x80000
	s_bfe_u32 s1, s1, 0x2000d
	s_add_i32 s1, s0, s1
	s_bfe_i32 s2, s1, 0x80000
	s_and_b32 s1, s1, 0xfc
	s_sub_i32 s0, s0, s1
	s_sext_i32_i16 s2, s2
	s_sext_i32_i8 s0, s0
	s_lshr_b32 s2, s2, 2
	s_add_i32 s14, s4, s0
	s_ashr_i32 s15, s14, 31
	s_bfe_i64 s[8:9], s[2:3], 0x100000
	s_lshl_b64 s[0:1], s[14:15], 19
	s_lshl_b64 s[8:9], s[8:9], 19
	s_add_u32 s68, s17, s8
	s_addc_u32 s69, s63, s9
	s_add_i32 s84, s81, 0
	v_lshl_or_b32 v134, v7, 11, v3
	v_lshl_or_b32 v136, v4, 11, v3
	v_lshl_or_b32 v137, v5, 11, v3
	s_mov_b64 s[8:9], s[68:69]
	s_add_i32 m0, s84, 0x10000
	v_mov_b32_e32 v3, v135
	v_mov_b32_e32 v4, v137
	global_load_lds_dwordx4 v3, s[8:9]
	s_add_i32 m0, s84, 0x12000
	v_writelane_b32 v254, s62, 24
	global_load_lds_dwordx4 v4, s[8:9]
	s_add_u32 s8, s68, 0x40000
	s_addc_u32 s9, s69, 0
	s_add_i32 m0, s84, 0x14000
	v_writelane_b32 v254, s96, 22
	global_load_lds_dwordx4 v3, s[8:9]
	s_add_i32 m0, s84, 0x16000
	s_add_u32 s70, s16, s0
	s_addc_u32 s71, s79, s1
	global_load_lds_dwordx4 v4, s[8:9]
	s_mov_b64 s[0:1], s[70:71]
	v_mov_b32_e32 v3, v134
	s_mov_b32 m0, s84
	s_add_i32 s85, s84, 0x2000
	v_mov_b32_e32 v4, v136
	global_load_lds_dwordx4 v3, s[0:1]
	s_mov_b32 m0, s85
	s_mov_b32 s88, 0
	global_load_lds_dwordx4 v4, s[0:1]
	s_add_u32 s0, s70, 0x40000
	s_addc_u32 s1, s71, 0
	s_add_i32 s86, s84, 0x4000
	s_mov_b32 m0, s86
	s_add_i32 s87, s84, 0x6000
	s_cmp_eq_u32 s5, 1
	global_load_lds_dwordx4 v3, s[0:1]
	s_mov_b32 m0, s87
	v_writelane_b32 v254, s97, 23
	global_load_lds_dwordx4 v4, s[0:1]
	s_cselect_b64 s[0:1], -1, 0
	s_cmp_lg_u32 s5, 1
	s_cbranch_scc1 .LBB0_322
	s_barrier

.Lmy_nopf_4:
	s_barrier
.LBB0_379:
	s_cmp_lt_i32 s60, 6
	s_cselect_b64 s[0:1], -1, 0
	s_cmp_gt_i32 s61, 5
	s_cselect_b64 s[2:3], -1, 0
	s_and_b64 s[0:1], s[0:1], s[2:3]
	s_andn2_b64 vcc, exec, s[0:1]
	s_cbranch_vccnz .LBB0_426
	v_readlane_b32 s0, v254, 18
	s_cmpk_gt_i32 s0, 0xff
	v_readlane_b32 s1, v254, 19
	s_cbranch_scc1 .LBB0_390
	s_add_u32 s2, s58, 0x8c00000
	v_readlane_b32 s0, v254, 18
	s_addc_u32 s3, s59, 0
	v_readlane_b32 s1, v254, 19
	s_lshl_b32 s0, s0, 6
	v_lshrrev_b32_e32 v92, 5, v0
	v_or_b32_e32 v94, 0x200, v0
	s_waitcnt vmcnt(0)
	v_or_b32_e32 v4, s0, v92
	s_movk_i32 s1, 0xc00
	v_mov_b64_e32 v[2:3], s[2:3]
	v_lshlrev_b32_e32 v88, 4, v0
	v_lshrrev_b32_e32 v91, 5, v94
	v_mad_i64_i32 v[4:5], s[4:5], v4, s1, v[2:3]
	v_and_b32_e32 v20, 0x1f0, v88
	v_mov_b32_e32 v21, 0
	v_or_b32_e32 v6, s0, v91
	v_or_b32_e32 v95, 0x400, v0
	v_lshl_add_u64 v[4:5], v[4:5], 0, v[20:21]
	v_mad_i64_i32 v[6:7], s[4:5], v6, s1, v[2:3]
	v_lshrrev_b32_e32 v90, 5, v95
	v_lshl_add_u64 v[6:7], v[6:7], 0, v[20:21]
	global_load_dwordx4 v[14:17], v[4:5], off offset:512
	global_load_dwordx4 v[10:13], v[6:7], off offset:512
	v_or_b32_e32 v4, s0, v90
	v_or_b32_e32 v96, 0x600, v0
	v_mad_i64_i32 v[4:5], s[4:5], v4, s1, v[2:3]
	v_lshrrev_b32_e32 v89, 5, v96
	v_lshl_add_u64 v[18:19], v[4:5], 0, v[20:21]
	v_or_b32_e32 v4, s0, v89
	v_mad_i64_i32 v[2:3], s[4:5], v4, s1, v[2:3]
	s_add_u32 s4, s58, 0x7c00000
	s_addc_u32 s5, s59, 0
	s_ashr_i32 s1, s0, 31
	s_lshl_b64 s[6:7], s[0:1], 6
	s_add_u32 s6, s58, s6
	v_lshlrev_b32_e32 v66, 3, v0
	s_addc_u32 s7, s59, s7
	v_mov_b32_e32 v67, v21
	v_lshl_add_u64 v[22:23], v[2:3], 0, v[20:21]
	global_load_dwordx4 v[6:9], v[18:19], off offset:512
	global_load_dwordx4 v[2:5], v[22:23], off offset:512
	v_lshl_add_u64 v[18:19], s[6:7], 0, v[66:67]
	s_mov_b32 s1, 0xf400000
	v_add_co_u32_e32 v22, vcc, s1, v18
	s_mov_b32 s1, 0xf500000
	s_nop 0
	v_addc_co_u32_e32 v23, vcc, 0, v19, vcc
	v_add_co_u32_e32 v24, vcc, s1, v18
	s_mov_b32 s1, 0xf600000
	s_nop 0
	v_addc_co_u32_e32 v25, vcc, 0, v19, vcc
	v_add_co_u32_e32 v26, vcc, s1, v18
	s_mov_b32 s1, 0xf700000
	s_nop 0
	v_addc_co_u32_e32 v27, vcc, 0, v19, vcc
	v_add_co_u32_e32 v18, vcc, s1, v18
	v_lshrrev_b32_e32 v93, 3, v0
	s_nop 0
	v_addc_co_u32_e32 v19, vcc, 0, v19, vcc
	global_load_dwordx2 v[68:69], v[22:23], off
	global_load_dwordx2 v[70:71], v[24:25], off
	global_load_dwordx2 v[72:73], v[26:27], off
	global_load_dwordx2 v[74:75], v[18:19], off
	v_and_b32_e32 v19, 56, v93
	v_mov_b32_e32 v20, 0xff8
	v_or_b32_e32 v78, s0, v19
	v_bitop3_b32 v19, s0, v20, v19 bitop3:0xc8
	v_lshlrev_b32_e32 v67, 1, v0
	v_and_b32_e32 v18, 0x1f8, v66
	v_cmp_ne_u32_e32 vcc, 0, v19
	v_ashrrev_i32_e32 v79, 31, v78
	s_and_saveexec_b64 s[6:7], vcc
	s_xor_b64 s[6:7], exec, s[6:7]
	s_cbranch_execz .LBB0_383
	v_lshlrev_b64 v[22:23], 10, v[78:79]
	v_lshlrev_b32_e32 v20, 1, v18
	v_lshl_add_u64 v[22:23], s[4:5], 0, v[22:23]
	v_lshl_add_u64 v[20:21], v[22:23], 0, v[20:21]
	global_load_dwordx4 v[62:65], v[20:21], off offset:-2048
	global_load_dwordx4 v[58:61], v[20:21], off offset:-1024

.Lmy_nopf_5:
	s_barrier
.LBB0_426:
	s_cmp_lt_i32 s60, 7
	s_cselect_b64 s[0:1], -1, 0
	s_cmp_gt_i32 s61, 6
	s_cselect_b64 s[2:3], -1, 0
	s_and_b64 s[0:1], s[0:1], s[2:3]
	s_andn2_b64 vcc, exec, s[0:1]
	v_readlane_b32 s20, v254, 18
	v_readlane_b32 s21, v254, 19
	s_cbranch_vccnz .LBB0_465
	s_add_u32 s4, s58, 0x180000
	s_addc_u32 s5, s59, 0
	s_lshl_b32 s0, s20, 9
	v_mov_b32_e32 v2, 0x7fff
	v_bitop3_b32 v3, s0, v2, v0 bitop3:0xc8
	s_lshl_b32 s0, s20, 2
	s_bfe_i32 s2, s20, 0x170000
	s_and_b32 s1, s0, 0xc0
	s_and_b32 s0, s2, 0xffffffc0
	s_lshl_b32 s2, s2, 8
	s_and_b32 s2, s2, 0xffffc000
	s_or_b32 s1, s2, s1
	v_or_b32_e32 v2, s1, v1
	s_ashr_i32 s1, s0, 31
	s_lshl_b64 s[0:1], s[0:1], 16
	s_waitcnt vmcnt(0)
	v_lshl_or_b32 v4, v3, 1, s0
	v_mov_b32_e32 v5, s1
	s_movk_i32 s12, 0x7fff
	v_or_b32_e32 v2, 0xf00, v2
	v_lshl_add_u64 v[4:5], s[58:59], 0, v[4:5]
	v_mov_b32_e32 v20, 0
	s_mov_b64 s[6:7], 0

.Lmy_nopf_6:
	s_barrier
.LBB0_465:
	s_cmp_lt_i32 s60, 8
	s_cselect_b64 s[0:1], -1, 0
	s_cmp_gt_i32 s61, 7
	s_cselect_b64 s[2:3], -1, 0
	s_and_b64 s[0:1], s[0:1], s[2:3]
	s_andn2_b64 vcc, exec, s[0:1]
	s_cbranch_vccnz .LBB0_512
	s_cmpk_gt_i32 s20, 0xff
	s_cbranch_scc1 .LBB0_476
	s_ashr_i32 s21, s20, 31
	s_lshl_b32 s4, s20, 6
	s_lshl_b64 s[0:1], s[20:21], 12
	s_add_u32 s0, s58, s0
	s_addc_u32 s1, s59, s1
	v_lshlrev_b32_e32 v78, 3, v0
	v_mov_b32_e32 v79, 0
	v_lshl_add_u64 v[2:3], s[0:1], 0, v[78:79]
	v_add_co_u32_e32 v2, vcc, 0x200000, v2
	v_and_b32_e32 v161, 0xff, v0
	s_nop 0
	v_addc_co_u32_e32 v3, vcc, 0, v3, vcc
	v_lshlrev_b32_e32 v150, 2, v161
	v_mov_b32_e32 v151, v79
	s_waitcnt vmcnt(0)
	v_readlane_b32 s98, v254, 20
	v_lshrrev_b32_e32 v246, 4, v1
	v_and_b32_e32 v247, 15, v1
	v_lshlrev_b32_e32 v246, 12, v246
	s_lshl_b32 s98, s98, 7
	v_lshl_add_u32 v247, v247, 2, s98
	v_add_u32_e32 v246, v246, v247
	global_load_dword v236, v246, s[40:41]
	global_load_dword v237, v246, s[40:41] offset:1024
	global_load_dword v238, v246, s[40:41] offset:2048
	global_load_dword v239, v246, s[40:41] offset:3072
	global_load_dword v240, v246, s[40:41] offset:64
	global_load_dword v241, v246, s[40:41] offset:1088
	global_load_dword v242, v246, s[40:41] offset:2112
	global_load_dword v243, v246, s[40:41] offset:3136
	global_load_dword v244, v247, s[42:43]
	global_load_dword v245, v247, s[42:43] offset:64
	global_load_dwordx2 v[164:165], v[2:3], off
	v_lshl_add_u64 v[2:3], s[40:41], 0, v[150:151]
	s_movk_i32 s0, 0x1000
	s_nop 0
	v_add_co_u32_e32 v4, vcc, s0, v2
	s_movk_i32 s0, 0x2000
	s_nop 0
	v_addc_co_u32_e32 v5, vcc, 0, v3, vcc
	v_add_co_u32_e32 v6, vcc, s0, v2
	v_lshlrev_b32_e32 v187, 2, v0
	s_nop 0
	v_addc_co_u32_e32 v7, vcc, 0, v3, vcc
	s_movk_i32 s0, 0x3000
	v_or_b32_e32 v8, 0xc00, v187
	v_add_co_u32_e32 v2, vcc, s0, v2
	s_add_u32 s0, s58, 0x8c00000
	v_or_b32_e32 v9, 0x1c00, v187
	v_or_b32_e32 v10, 0x2c00, v187
	v_addc_co_u32_e32 v3, vcc, 0, v3, vcc
	global_load_dword v142, v8, s[40:41]
	global_load_dword v147, v[4:5], off offset:1024
	global_load_dword v145, v[4:5], off offset:2048
	global_load_dword v143, v9, s[40:41]
	global_load_dword v134, v10, s[40:41]
	global_load_dword v139, v[2:3], off
	global_load_dword v141, v[2:3], off offset:1024
	global_load_dword v137, v[2:3], off offset:2048
	v_or_b32_e32 v2, 0x3c00, v187
	s_addc_u32 s1, s59, 0
	v_lshrrev_b32_e32 v160, 5, v0
	s_movk_i32 s12, 0xc00
	global_load_dword v135, v2, s[40:41]
	global_load_dword v148, v150, s[40:41]
	global_load_dword v146, v150, s[40:41] offset:1024
	global_load_dword v144, v150, s[40:41] offset:2048
	global_load_dword v149, v[6:7], off offset:-4096
	global_load_dword v138, v[6:7], off
	global_load_dword v140, v[6:7], off offset:1024
	global_load_dword v136, v[6:7], off offset:2048
	global_load_dword v162, v150, s[42:43]
	v_or_b32_e32 v2, s4, v160
	v_mov_b64_e32 v[18:19], s[0:1]
	v_lshlrev_b32_e32 v6, 4, v0
	v_mad_i64_i32 v[2:3], s[2:3], v2, s12, v[18:19]
	v_and_b32_e32 v4, 0x1f0, v6
	v_mov_b32_e32 v5, v79
	v_or_b32_e32 v7, 0x200, v0
	v_lshl_add_u64 v[2:3], v[2:3], 0, v[4:5]
	v_lshrrev_b32_e32 v159, 5, v7
	global_load_dwordx4 v[74:77], v[2:3], off
	global_load_dwordx4 v[70:73], v[2:3], off offset:512
	v_or_b32_e32 v2, s4, v159
	v_mad_i64_i32 v[2:3], s[2:3], v2, s12, v[18:19]
	v_or_b32_e32 v20, 0x400, v0
	v_lshl_add_u64 v[2:3], v[2:3], 0, v[4:5]
	v_lshrrev_b32_e32 v158, 5, v20
	global_load_dwordx4 v[66:69], v[2:3], off
	global_load_dwordx4 v[62:65], v[2:3], off offset:512
	v_or_b32_e32 v2, s4, v158
	v_mad_i64_i32 v[2:3], s[2:3], v2, s12, v[18:19]
	v_or_b32_e32 v22, 0x600, v0
	v_lshl_add_u64 v[2:3], v[2:3], 0, v[4:5]
	v_lshrrev_b32_e32 v151, 5, v22
	global_load_dwordx4 v[58:61], v[2:3], off
	global_load_dwordx4 v[54:57], v[2:3], off offset:512
	v_or_b32_e32 v2, s4, v151
	v_mad_i64_i32 v[2:3], s[2:3], v2, s12, v[18:19]
	v_lshrrev_b32_e32 v152, 6, v0
	v_lshl_add_u64 v[2:3], v[2:3], 0, v[4:5]
	v_or_b32_e32 v24, s4, v152
	global_load_dwordx4 v[50:53], v[2:3], off
	global_load_dwordx4 v[10:13], v[2:3], off offset:512
	v_mad_i64_i32 v[2:3], s[2:3], v24, s12, v[18:19]
	v_and_b32_e32 v80, 0x3f0, v6
	v_mov_b32_e32 v81, v79
	v_lshrrev_b32_e32 v153, 6, v7
	v_lshl_add_u64 v[14:15], v[2:3], 0, v[80:81]
	v_or_b32_e32 v2, s4, v153
	v_mad_i64_i32 v[2:3], s[2:3], v2, s12, v[18:19]
	v_lshrrev_b32_e32 v154, 6, v20
	v_lshl_add_u64 v[16:17], v[2:3], 0, v[80:81]
	global_load_dwordx4 v[6:9], v[14:15], off offset:1024
	global_load_dwordx4 v[2:5], v[16:17], off offset:1024
	v_or_b32_e32 v14, s4, v154
	v_mad_i64_i32 v[14:15], s[2:3], v14, s12, v[18:19]
	v_lshrrev_b32_e32 v155, 6, v22
	v_lshl_add_u64 v[20:21], v[14:15], 0, v[80:81]
	v_or_b32_e32 v14, s4, v155
	v_mad_i64_i32 v[14:15], s[2:3], v14, s12, v[18:19]
	v_lshl_add_u64 v[22:23], v[14:15], 0, v[80:81]
	global_load_dwordx4 v[30:33], v[20:21], off offset:1024
	global_load_dwordx4 v[14:17], v[22:23], off offset:1024
	v_or_b32_e32 v22, 0xa00, v0
	v_lshrrev_b32_e32 v156, 6, v22
	v_or_b32_e32 v20, 32, v24
	v_or_b32_e32 v22, s4, v156
	v_mad_i64_i32 v[20:21], s[2:3], v20, s12, v[18:19]
	v_mad_i64_i32 v[22:23], s[2:3], v22, s12, v[18:19]
	v_lshl_add_u64 v[20:21], v[20:21], 0, v[80:81]
	v_lshl_add_u64 v[22:23], v[22:23], 0, v[80:81]
	global_load_dwordx4 v[38:41], v[20:21], off offset:1024
	global_load_dwordx4 v[34:37], v[22:23], off offset:1024
	v_or_b32_e32 v22, 0xe00, v0
	v_lshrrev_b32_e32 v157, 6, v22
	v_or_b32_e32 v20, 48, v24
	v_or_b32_e32 v22, s4, v157
	v_mad_i64_i32 v[20:21], s[2:3], v20, s12, v[18:19]
	v_mad_i64_i32 v[18:19], s[2:3], v22, s12, v[18:19]
	v_readlane_b32 s2, v254, 21
	s_lshr_b32 s2, s2, 7
	s_lshl_b32 s3, s20, 2
	s_add_i32 s2, s3, s2
	s_ashr_i32 s3, s2, 31
	s_lshl_b64 s[2:3], s[2:3], 14
	v_lshrrev_b32_e32 v166, 5, v1
	s_add_u32 s2, s58, s2
	s_addc_u32 s3, s59, s3
	v_lshlrev_b32_e32 v182, 4, v166
	v_mov_b32_e32 v183, v79
	v_lshl_add_u64 v[82:83], s[2:3], 0, v[182:183]
	s_mov_b64 s[2:3], 0xe400000
	v_and_b32_e32 v185, 31, v0
	v_lshl_add_u64 v[26:27], v[82:83], 0, s[2:3]
	s_mov_b64 s[2:3], 0xe400020
	v_lshlrev_b32_e32 v28, 7, v185
	v_lshl_add_u64 v[94:95], v[82:83], 0, s[2:3]
	s_mov_b64 s[2:3], 0xe400040
	v_mov_b32_e32 v29, v79
	v_or_b32_e32 v114, 0x1000, v28
	v_mov_b32_e32 v115, v79
	v_or_b32_e32 v116, 0x2000, v28
	v_mov_b32_e32 v117, v79
	v_or_b32_e32 v168, 0x3000, v28
	v_mov_b32_e32 v169, v79
	v_lshl_add_u64 v[118:119], v[82:83], 0, s[2:3]
	s_mov_b64 s[2:3], 0xe400060
	v_lshl_add_u64 v[20:21], v[20:21], 0, v[80:81]
	v_lshl_add_u64 v[18:19], v[18:19], 0, v[80:81]
	v_lshl_add_u64 v[84:85], v[26:27], 0, v[28:29]
	v_lshl_add_u64 v[86:87], v[26:27], 0, v[114:115]
	v_lshl_add_u64 v[88:89], v[26:27], 0, v[116:117]
	v_lshl_add_u64 v[90:91], v[26:27], 0, v[168:169]
	v_lshl_add_u64 v[92:93], v[94:95], 0, v[114:115]
	v_lshl_add_u64 v[96:97], v[94:95], 0, v[116:117]
	v_lshl_add_u64 v[94:95], v[94:95], 0, v[168:169]
	v_lshl_add_u64 v[106:107], v[118:119], 0, v[114:115]
	v_lshl_add_u64 v[108:109], v[118:119], 0, v[116:117]
	v_lshl_add_u64 v[82:83], v[82:83], 0, s[2:3]
	global_load_dwordx4 v[46:49], v[20:21], off offset:1024
	global_load_dwordx4 v[42:45], v[18:19], off offset:1024
	s_nop 0
	global_load_dwordx4 v[18:21], v[86:87], off
	global_load_dwordx4 v[22:25], v[88:89], off
	global_load_dwordx4 v[26:29], v[84:85], off
	s_nop 0
	global_load_dwordx4 v[86:89], v[84:85], off offset:32
	global_load_dwordx4 v[102:105], v[90:91], off
	s_nop 0
	global_load_dwordx4 v[90:93], v[92:93], off
	s_nop 0
	global_load_dwordx4 v[98:101], v[96:97], off
	s_nop 0
	global_load_dwordx4 v[94:97], v[94:95], off
	s_nop 0
	global_load_dwordx4 v[110:113], v[106:107], off
	s_nop 0
	global_load_dwordx4 v[106:109], v[108:109], off
	v_lshl_add_u64 v[122:123], v[118:119], 0, v[168:169]
	global_load_dwordx4 v[130:133], v[84:85], off offset:64
	global_load_dwordx4 v[118:121], v[84:85], off offset:96
	v_lshl_add_u64 v[84:85], v[82:83], 0, v[114:115]
	global_load_dwordx4 v[126:129], v[122:123], off
	s_nop 0
	global_load_dwordx4 v[122:125], v[84:85], off
	v_lshl_add_u64 v[84:85], v[82:83], 0, v[116:117]
	v_lshl_add_u64 v[82:83], v[82:83], 0, v[168:169]
	global_load_dwordx4 v[114:117], v[84:85], off
	s_nop 0
	global_load_dwordx4 v[82:85], v[82:83], off
	s_add_i32 s2, 0, 0x23000
	v_lshrrev_b32_e32 v81, 3, v0
	v_add_u32_e32 v78, s2, v78
	v_and_b32_e32 v163, 32, v81
	s_waitcnt vmcnt(49)
	ds_write_b64 v78, v[164:165]
	v_lshl_add_u32 v78, v163, 6, s2
	s_waitcnt lgkmcnt(0)
	s_barrier
	v_lshrrev_b32_e32 v247, 4, v1
	v_and_b32_e32 v246, 15, v1
	v_lshlrev_b32_e32 v248, 6, v246
	v_lshl_add_u32 v248, v247, 4, v248
	v_add_u32_e32 v248, 0x23000, v248
	ds_read_b128 v[220:223], v248
	ds_read_b128 v[224:227], v248 offset:1024
	ds_read_b128 v[228:231], v248 offset:2048
	ds_read_b128 v[232:235], v248 offset:3072
	v_readlane_b32 s98, v254, 20
	v_lshlrev_b32_e32 v249, 12, v247
	v_lshl_add_u32 v249, v246, 2, v249
	s_lshl_b32 s99, s98, 7
	v_add_u32_e32 v249, s99, v249
	s_waitcnt lgkmcnt(0)
	v_mfma_f32_16x16x4_f32 v[188:191], v220, v236, 0
	v_mfma_f32_16x16x4_f32 v[192:195], v220, v240, 0
	v_mfma_f32_16x16x4_f32 v[196:199], v224, v236, 0
	v_mfma_f32_16x16x4_f32 v[200:203], v224, v240, 0
	v_mfma_f32_16x16x4_f32 v[204:207], v228, v236, 0
	v_mfma_f32_16x16x4_f32 v[208:211], v228, v240, 0
	v_mfma_f32_16x16x4_f32 v[212:215], v232, v236, 0
	v_mfma_f32_16x16x4_f32 v[216:219], v232, v240, 0
	v_mfma_f32_16x16x4_f32 v[188:191], v221, v237, v[188:191]
	v_mfma_f32_16x16x4_f32 v[192:195], v221, v241, v[192:195]
	v_mfma_f32_16x16x4_f32 v[196:199], v225, v237, v[196:199]
	v_mfma_f32_16x16x4_f32 v[200:203], v225, v241, v[200:203]
	v_mfma_f32_16x16x4_f32 v[204:207], v229, v237, v[204:207]
	v_mfma_f32_16x16x4_f32 v[208:211], v229, v241, v[208:211]
	v_mfma_f32_16x16x4_f32 v[212:215], v233, v237, v[212:215]
	v_mfma_f32_16x16x4_f32 v[216:219], v233, v241, v[216:219]
	v_mfma_f32_16x16x4_f32 v[188:191], v222, v238, v[188:191]
	v_mfma_f32_16x16x4_f32 v[192:195], v222, v242, v[192:195]
	v_mfma_f32_16x16x4_f32 v[196:199], v226, v238, v[196:199]
	v_mfma_f32_16x16x4_f32 v[200:203], v226, v242, v[200:203]
	v_mfma_f32_16x16x4_f32 v[204:207], v230, v238, v[204:207]
	v_mfma_f32_16x16x4_f32 v[208:211], v230, v242, v[208:211]
	v_mfma_f32_16x16x4_f32 v[212:215], v234, v238, v[212:215]
	v_mfma_f32_16x16x4_f32 v[216:219], v234, v242, v[216:219]
	v_mfma_f32_16x16x4_f32 v[188:191], v223, v239, v[188:191]
	v_mfma_f32_16x16x4_f32 v[192:195], v223, v243, v[192:195]
	v_mfma_f32_16x16x4_f32 v[196:199], v227, v239, v[196:199]
	v_mfma_f32_16x16x4_f32 v[200:203], v227, v243, v[200:203]
	v_mfma_f32_16x16x4_f32 v[204:207], v231, v239, v[204:207]
	v_mfma_f32_16x16x4_f32 v[208:211], v231, v243, v[208:211]
	v_mfma_f32_16x16x4_f32 v[212:215], v235, v239, v[212:215]
	v_mfma_f32_16x16x4_f32 v[216:219], v235, v243, v[216:219]
	s_nop 7
	s_nop 3
	v_add_f32_e32 v188, v188, v244
	v_add_f32_e32 v189, v189, v244
	v_add_f32_e32 v190, v190, v244
	v_add_f32_e32 v191, v191, v244
	v_max_f32_e32 v188, 0xc2a00000, v188
	v_max_f32_e32 v189, 0xc2a00000, v189
	v_max_f32_e32 v190, 0xc2a00000, v190
	v_max_f32_e32 v191, 0xc2a00000, v191
	v_mul_f32_e32 v188, 0xbfb8aa3b, v188
	v_mul_f32_e32 v189, 0xbfb8aa3b, v189
	v_mul_f32_e32 v190, 0xbfb8aa3b, v190
	v_mul_f32_e32 v191, 0xbfb8aa3b, v191
	v_exp_f32_e32 v188, v188
	v_exp_f32_e32 v189, v189
	v_exp_f32_e32 v190, v190
	v_exp_f32_e32 v191, v191
	v_add_f32_e32 v188, 1.0, v188
	v_add_f32_e32 v189, 1.0, v189
	v_add_f32_e32 v190, 1.0, v190
	v_add_f32_e32 v191, 1.0, v191
	v_log_f32_e32 v188, v188
	v_log_f32_e32 v189, v189
	v_log_f32_e32 v190, v190
	v_log_f32_e32 v191, v191
	v_mul_f32_e32 v188, 0x3f317218, v188
	v_mul_f32_e32 v189, 0x3f317218, v189
	v_mul_f32_e32 v190, 0x3f317218, v190
	v_mul_f32_e32 v191, 0x3f317218, v191
	ds_write_b32 v249, v188 offset:0
	ds_write_b32 v249, v189 offset:1024
	ds_write_b32 v249, v190 offset:2048
	ds_write_b32 v249, v191 offset:3072
	v_add_f32_e32 v192, v192, v245
	v_add_f32_e32 v193, v193, v245
	v_add_f32_e32 v194, v194, v245
	v_add_f32_e32 v195, v195, v245
	v_max_f32_e32 v192, 0xc2a00000, v192
	v_max_f32_e32 v193, 0xc2a00000, v193
	v_max_f32_e32 v194, 0xc2a00000, v194
	v_max_f32_e32 v195, 0xc2a00000, v195
	v_mul_f32_e32 v192, 0xbfb8aa3b, v192
	v_mul_f32_e32 v193, 0xbfb8aa3b, v193
	v_mul_f32_e32 v194, 0xbfb8aa3b, v194
	v_mul_f32_e32 v195, 0xbfb8aa3b, v195
	v_exp_f32_e32 v192, v192
	v_exp_f32_e32 v193, v193
	v_exp_f32_e32 v194, v194
	v_exp_f32_e32 v195, v195
	v_add_f32_e32 v192, 1.0, v192
	v_add_f32_e32 v193, 1.0, v193
	v_add_f32_e32 v194, 1.0, v194
	v_add_f32_e32 v195, 1.0, v195
	v_log_f32_e32 v192, v192
	v_log_f32_e32 v193, v193
	v_log_f32_e32 v194, v194
	v_log_f32_e32 v195, v195
	v_mul_f32_e32 v192, 0x3f317218, v192
	v_mul_f32_e32 v193, 0x3f317218, v193
	v_mul_f32_e32 v194, 0x3f317218, v194
	v_mul_f32_e32 v195, 0x3f317218, v195
	ds_write_b32 v249, v192 offset:64
	ds_write_b32 v249, v193 offset:1088
	ds_write_b32 v249, v194 offset:2112
	ds_write_b32 v249, v195 offset:3136
	v_add_f32_e32 v196, v196, v244
	v_add_f32_e32 v197, v197, v244
	v_add_f32_e32 v198, v198, v244
	v_add_f32_e32 v199, v199, v244
	v_max_f32_e32 v196, 0xc2a00000, v196
	v_max_f32_e32 v197, 0xc2a00000, v197
	v_max_f32_e32 v198, 0xc2a00000, v198
	v_max_f32_e32 v199, 0xc2a00000, v199
	v_mul_f32_e32 v196, 0xbfb8aa3b, v196
	v_mul_f32_e32 v197, 0xbfb8aa3b, v197
	v_mul_f32_e32 v198, 0xbfb8aa3b, v198
	v_mul_f32_e32 v199, 0xbfb8aa3b, v199
	v_exp_f32_e32 v196, v196
	v_exp_f32_e32 v197, v197
	v_exp_f32_e32 v198, v198
	v_exp_f32_e32 v199, v199
	v_add_f32_e32 v196, 1.0, v196
	v_add_f32_e32 v197, 1.0, v197
	v_add_f32_e32 v198, 1.0, v198
	v_add_f32_e32 v199, 1.0, v199
	v_log_f32_e32 v196, v196
	v_log_f32_e32 v197, v197
	v_log_f32_e32 v198, v198
	v_log_f32_e32 v199, v199
	v_mul_f32_e32 v196, 0x3f317218, v196
	v_mul_f32_e32 v197, 0x3f317218, v197
	v_mul_f32_e32 v198, 0x3f317218, v198
	v_mul_f32_e32 v199, 0x3f317218, v199
	ds_write_b32 v249, v196 offset:16384
	ds_write_b32 v249, v197 offset:17408
	ds_write_b32 v249, v198 offset:18432
	ds_write_b32 v249, v199 offset:19456
	v_add_f32_e32 v200, v200, v245
	v_add_f32_e32 v201, v201, v245
	v_add_f32_e32 v202, v202, v245
	v_add_f32_e32 v203, v203, v245
	v_max_f32_e32 v200, 0xc2a00000, v200
	v_max_f32_e32 v201, 0xc2a00000, v201
	v_max_f32_e32 v202, 0xc2a00000, v202
	v_max_f32_e32 v203, 0xc2a00000, v203
	v_mul_f32_e32 v200, 0xbfb8aa3b, v200
	v_mul_f32_e32 v201, 0xbfb8aa3b, v201
	v_mul_f32_e32 v202, 0xbfb8aa3b, v202
	v_mul_f32_e32 v203, 0xbfb8aa3b, v203
	v_exp_f32_e32 v200, v200
	v_exp_f32_e32 v201, v201
	v_exp_f32_e32 v202, v202
	v_exp_f32_e32 v203, v203
	v_add_f32_e32 v200, 1.0, v200
	v_add_f32_e32 v201, 1.0, v201
	v_add_f32_e32 v202, 1.0, v202
	v_add_f32_e32 v203, 1.0, v203
	v_log_f32_e32 v200, v200
	v_log_f32_e32 v201, v201
	v_log_f32_e32 v202, v202
	v_log_f32_e32 v203, v203
	v_mul_f32_e32 v200, 0x3f317218, v200
	v_mul_f32_e32 v201, 0x3f317218, v201
	v_mul_f32_e32 v202, 0x3f317218, v202
	v_mul_f32_e32 v203, 0x3f317218, v203
	ds_write_b32 v249, v200 offset:16448
	ds_write_b32 v249, v201 offset:17472
	ds_write_b32 v249, v202 offset:18496
	ds_write_b32 v249, v203 offset:19520
	v_add_f32_e32 v204, v204, v244
	v_add_f32_e32 v205, v205, v244
	v_add_f32_e32 v206, v206, v244
	v_add_f32_e32 v207, v207, v244
	v_max_f32_e32 v204, 0xc2a00000, v204
	v_max_f32_e32 v205, 0xc2a00000, v205
	v_max_f32_e32 v206, 0xc2a00000, v206
	v_max_f32_e32 v207, 0xc2a00000, v207
	v_mul_f32_e32 v204, 0xbfb8aa3b, v204
	v_mul_f32_e32 v205, 0xbfb8aa3b, v205
	v_mul_f32_e32 v206, 0xbfb8aa3b, v206
	v_mul_f32_e32 v207, 0xbfb8aa3b, v207
	v_exp_f32_e32 v204, v204
	v_exp_f32_e32 v205, v205
	v_exp_f32_e32 v206, v206
	v_exp_f32_e32 v207, v207
	v_add_f32_e32 v204, 1.0, v204
	v_add_f32_e32 v205, 1.0, v205
	v_add_f32_e32 v206, 1.0, v206
	v_add_f32_e32 v207, 1.0, v207
	v_log_f32_e32 v204, v204
	v_log_f32_e32 v205, v205
	v_log_f32_e32 v206, v206
	v_log_f32_e32 v207, v207
	v_mul_f32_e32 v204, 0x3f317218, v204
	v_mul_f32_e32 v205, 0x3f317218, v205
	v_mul_f32_e32 v206, 0x3f317218, v206
	v_mul_f32_e32 v207, 0x3f317218, v207
	ds_write_b32 v249, v204 offset:32768
	ds_write_b32 v249, v205 offset:33792
	ds_write_b32 v249, v206 offset:34816
	ds_write_b32 v249, v207 offset:35840
	v_add_f32_e32 v208, v208, v245
	v_add_f32_e32 v209, v209, v245
	v_add_f32_e32 v210, v210, v245
	v_add_f32_e32 v211, v211, v245
	v_max_f32_e32 v208, 0xc2a00000, v208
	v_max_f32_e32 v209, 0xc2a00000, v209
	v_max_f32_e32 v210, 0xc2a00000, v210
	v_max_f32_e32 v211, 0xc2a00000, v211
	v_mul_f32_e32 v208, 0xbfb8aa3b, v208
	v_mul_f32_e32 v209, 0xbfb8aa3b, v209
	v_mul_f32_e32 v210, 0xbfb8aa3b, v210
	v_mul_f32_e32 v211, 0xbfb8aa3b, v211
	v_exp_f32_e32 v208, v208
	v_exp_f32_e32 v209, v209
	v_exp_f32_e32 v210, v210
	v_exp_f32_e32 v211, v211
	v_add_f32_e32 v208, 1.0, v208
	v_add_f32_e32 v209, 1.0, v209
	v_add_f32_e32 v210, 1.0, v210
	v_add_f32_e32 v211, 1.0, v211
	v_log_f32_e32 v208, v208
	v_log_f32_e32 v209, v209
	v_log_f32_e32 v210, v210
	v_log_f32_e32 v211, v211
	v_mul_f32_e32 v208, 0x3f317218, v208
	v_mul_f32_e32 v209, 0x3f317218, v209
	v_mul_f32_e32 v210, 0x3f317218, v210
	v_mul_f32_e32 v211, 0x3f317218, v211
	ds_write_b32 v249, v208 offset:32832
	ds_write_b32 v249, v209 offset:33856
	ds_write_b32 v249, v210 offset:34880
	ds_write_b32 v249, v211 offset:35904
	v_add_f32_e32 v212, v212, v244
	v_add_f32_e32 v213, v213, v244
	v_add_f32_e32 v214, v214, v244
	v_add_f32_e32 v215, v215, v244
	v_max_f32_e32 v212, 0xc2a00000, v212
	v_max_f32_e32 v213, 0xc2a00000, v213
	v_max_f32_e32 v214, 0xc2a00000, v214
	v_max_f32_e32 v215, 0xc2a00000, v215
	v_mul_f32_e32 v212, 0xbfb8aa3b, v212
	v_mul_f32_e32 v213, 0xbfb8aa3b, v213
	v_mul_f32_e32 v214, 0xbfb8aa3b, v214
	v_mul_f32_e32 v215, 0xbfb8aa3b, v215
	v_exp_f32_e32 v212, v212
	v_exp_f32_e32 v213, v213
	v_exp_f32_e32 v214, v214
	v_exp_f32_e32 v215, v215
	v_add_f32_e32 v212, 1.0, v212
	v_add_f32_e32 v213, 1.0, v213
	v_add_f32_e32 v214, 1.0, v214
	v_add_f32_e32 v215, 1.0, v215
	v_log_f32_e32 v212, v212
	v_log_f32_e32 v213, v213
	v_log_f32_e32 v214, v214
	v_log_f32_e32 v215, v215
	v_mul_f32_e32 v212, 0x3f317218, v212
	v_mul_f32_e32 v213, 0x3f317218, v213
	v_mul_f32_e32 v214, 0x3f317218, v214
	v_mul_f32_e32 v215, 0x3f317218, v215
	ds_write_b32 v249, v212 offset:49152
	ds_write_b32 v249, v213 offset:50176
	ds_write_b32 v249, v214 offset:51200
	ds_write_b32 v249, v215 offset:52224
	v_add_f32_e32 v216, v216, v245
	v_add_f32_e32 v217, v217, v245
	v_add_f32_e32 v218, v218, v245
	v_add_f32_e32 v219, v219, v245
	v_max_f32_e32 v216, 0xc2a00000, v216
	v_max_f32_e32 v217, 0xc2a00000, v217
	v_max_f32_e32 v218, 0xc2a00000, v218
	v_max_f32_e32 v219, 0xc2a00000, v219
	v_mul_f32_e32 v216, 0xbfb8aa3b, v216
	v_mul_f32_e32 v217, 0xbfb8aa3b, v217
	v_mul_f32_e32 v218, 0xbfb8aa3b, v218
	v_mul_f32_e32 v219, 0xbfb8aa3b, v219
	v_exp_f32_e32 v216, v216
	v_exp_f32_e32 v217, v217
	v_exp_f32_e32 v218, v218
	v_exp_f32_e32 v219, v219
	v_add_f32_e32 v216, 1.0, v216
	v_add_f32_e32 v217, 1.0, v217
	v_add_f32_e32 v218, 1.0, v218
	v_add_f32_e32 v219, 1.0, v219
	v_log_f32_e32 v216, v216
	v_log_f32_e32 v217, v217
	v_log_f32_e32 v218, v218
	v_log_f32_e32 v219, v219
	v_mul_f32_e32 v216, 0x3f317218, v216
	v_mul_f32_e32 v217, 0x3f317218, v217
	v_mul_f32_e32 v218, 0x3f317218, v218
	v_mul_f32_e32 v219, 0x3f317218, v219
	ds_write_b32 v249, v216 offset:49216
	ds_write_b32 v249, v217 offset:50240
	ds_write_b32 v249, v218 offset:51264
	ds_write_b32 v249, v219 offset:52288
	s_waitcnt lgkmcnt(0)
	s_barrier
	v_and_b32_e32 v246, 0xff, v0
	s_lshr_b32 s99, s98, 2
	s_lshl_b32 s100, s99, 15
	v_lshl_add_u32 v248, v246, 2, s100
	v_mov_b32_e32 v247, 0
	ds_read_b32 v220, v248 offset:0
	ds_read_b32 v221, v248 offset:1024
	ds_read_b32 v222, v248 offset:2048
	ds_read_b32 v223, v248 offset:3072
	ds_read_b32 v224, v248 offset:4096
	ds_read_b32 v225, v248 offset:5120
	ds_read_b32 v226, v248 offset:6144
	ds_read_b32 v227, v248 offset:7168
	s_waitcnt lgkmcnt(7)
	v_fmac_f32_e32 v247, 0xbd800000, v220
	ds_write_b32 v248, v247 offset:0
	s_waitcnt lgkmcnt(7)
	v_fmac_f32_e32 v247, 0xbd800000, v221
	ds_write_b32 v248, v247 offset:1024
	s_waitcnt lgkmcnt(7)
	v_fmac_f32_e32 v247, 0xbd800000, v222
	ds_write_b32 v248, v247 offset:2048
	s_waitcnt lgkmcnt(7)
	v_fmac_f32_e32 v247, 0xbd800000, v223
	ds_write_b32 v248, v247 offset:3072
	s_waitcnt lgkmcnt(7)
	v_fmac_f32_e32 v247, 0xbd800000, v224
	ds_write_b32 v248, v247 offset:4096
	s_waitcnt lgkmcnt(7)
	v_fmac_f32_e32 v247, 0xbd800000, v225
	ds_write_b32 v248, v247 offset:5120
	s_waitcnt lgkmcnt(7)
	v_fmac_f32_e32 v247, 0xbd800000, v226
	ds_write_b32 v248, v247 offset:6144
	s_waitcnt lgkmcnt(7)
	v_fmac_f32_e32 v247, 0xbd800000, v227
	ds_write_b32 v248, v247 offset:7168
	s_waitcnt lgkmcnt(4)
	ds_read_b32 v220, v248 offset:8192
	ds_read_b32 v221, v248 offset:9216
	ds_read_b32 v222, v248 offset:10240
	ds_read_b32 v223, v248 offset:11264
	ds_read_b32 v224, v248 offset:12288
	ds_read_b32 v225, v248 offset:13312
	ds_read_b32 v226, v248 offset:14336
	ds_read_b32 v227, v248 offset:15360
	s_waitcnt lgkmcnt(7)
	v_fmac_f32_e32 v247, 0xbd800000, v220
	ds_write_b32 v248, v247 offset:8192
	s_waitcnt lgkmcnt(7)
	v_fmac_f32_e32 v247, 0xbd800000, v221
	ds_write_b32 v248, v247 offset:9216
	s_waitcnt lgkmcnt(7)
	v_fmac_f32_e32 v247, 0xbd800000, v222
	ds_write_b32 v248, v247 offset:10240
	s_waitcnt lgkmcnt(7)
	v_fmac_f32_e32 v247, 0xbd800000, v223
	ds_write_b32 v248, v247 offset:11264
	s_waitcnt lgkmcnt(7)
	v_fmac_f32_e32 v247, 0xbd800000, v224
	ds_write_b32 v248, v247 offset:12288
	s_waitcnt lgkmcnt(7)
	v_fmac_f32_e32 v247, 0xbd800000, v225
	ds_write_b32 v248, v247 offset:13312
	s_waitcnt lgkmcnt(7)
	v_fmac_f32_e32 v247, 0xbd800000, v226
	ds_write_b32 v248, v247 offset:14336
	s_waitcnt lgkmcnt(7)
	v_fmac_f32_e32 v247, 0xbd800000, v227
	ds_write_b32 v248, v247 offset:15360
	s_waitcnt lgkmcnt(4)
	ds_read_b32 v220, v248 offset:16384
	ds_read_b32 v221, v248 offset:17408
	ds_read_b32 v222, v248 offset:18432
	ds_read_b32 v223, v248 offset:19456
	ds_read_b32 v224, v248 offset:20480
	ds_read_b32 v225, v248 offset:21504
	ds_read_b32 v226, v248 offset:22528
	ds_read_b32 v227, v248 offset:23552
	s_waitcnt lgkmcnt(7)
	v_fmac_f32_e32 v247, 0xbd800000, v220
	ds_write_b32 v248, v247 offset:16384
	s_waitcnt lgkmcnt(7)
	v_fmac_f32_e32 v247, 0xbd800000, v221
	ds_write_b32 v248, v247 offset:17408
	s_waitcnt lgkmcnt(7)
	v_fmac_f32_e32 v247, 0xbd800000, v222
	ds_write_b32 v248, v247 offset:18432
	s_waitcnt lgkmcnt(7)
	v_fmac_f32_e32 v247, 0xbd800000, v223
	ds_write_b32 v248, v247 offset:19456
	s_waitcnt lgkmcnt(7)
	v_fmac_f32_e32 v247, 0xbd800000, v224
	ds_write_b32 v248, v247 offset:20480
	s_waitcnt lgkmcnt(7)
	v_fmac_f32_e32 v247, 0xbd800000, v225
	ds_write_b32 v248, v247 offset:21504
	s_waitcnt lgkmcnt(7)
	v_fmac_f32_e32 v247, 0xbd800000, v226
	ds_write_b32 v248, v247 offset:22528
	s_waitcnt lgkmcnt(7)
	v_fmac_f32_e32 v247, 0xbd800000, v227
	ds_write_b32 v248, v247 offset:23552
	s_waitcnt lgkmcnt(4)
	ds_read_b32 v220, v248 offset:24576
	ds_read_b32 v221, v248 offset:25600
	ds_read_b32 v222, v248 offset:26624
	ds_read_b32 v223, v248 offset:27648
	ds_read_b32 v224, v248 offset:28672
	ds_read_b32 v225, v248 offset:29696
	ds_read_b32 v226, v248 offset:30720
	ds_read_b32 v227, v248 offset:31744
	s_waitcnt lgkmcnt(7)
	v_fmac_f32_e32 v247, 0xbd800000, v220
	ds_write_b32 v248, v247 offset:24576
	s_waitcnt lgkmcnt(7)
	v_fmac_f32_e32 v247, 0xbd800000, v221
	ds_write_b32 v248, v247 offset:25600
	s_waitcnt lgkmcnt(7)
	v_fmac_f32_e32 v247, 0xbd800000, v222
	ds_write_b32 v248, v247 offset:26624
	s_waitcnt lgkmcnt(7)
	v_fmac_f32_e32 v247, 0xbd800000, v223
	ds_write_b32 v248, v247 offset:27648
	s_waitcnt lgkmcnt(7)
	v_fmac_f32_e32 v247, 0xbd800000, v224
	ds_write_b32 v248, v247 offset:28672
	s_waitcnt lgkmcnt(7)
	v_fmac_f32_e32 v247, 0xbd800000, v225
	ds_write_b32 v248, v247 offset:29696
	s_waitcnt lgkmcnt(7)
	v_fmac_f32_e32 v247, 0xbd800000, v226
	ds_write_b32 v248, v247 offset:30720
	s_waitcnt lgkmcnt(7)
	v_fmac_f32_e32 v247, 0xbd800000, v227
	ds_write_b32 v248, v247 offset:31744
	s_cmp_lg_u32 s99, 0
	s_cbranch_scc1 .Lcb_notot_p7
	v_lshl_add_u32 v246, v246, 2, 0
	v_add_u32_e32 v246, 0x24000, v246
	ds_write_b32 v246, v247

.Lmy_nopf_7:
	s_barrier
.LBB0_512:
	s_cmp_lt_i32 s60, 9
	s_cselect_b64 s[0:1], -1, 0
	s_cmp_gt_i32 s61, 8
	s_cselect_b64 s[2:3], -1, 0
	s_and_b64 s[0:1], s[0:1], s[2:3]
	s_andn2_b64 vcc, exec, s[0:1]
	s_cbranch_vccnz .LBB0_609
	s_cmpk_gt_i32 s10, 0xff
	v_readfirstlane_b32 s45, v0
	s_cbranch_scc1 .LBB0_573
	s_mov_b32 s78, s62
	s_ashr_i32 s62, s10, 31
	s_lshr_b32 s0, s62, 29
	s_add_i32 s3, s10, s0
	s_and_b32 s0, s3, -8
	s_sub_i32 s4, s10, s0
	s_cmp_gt_i32 s4, -1
	s_cbranch_scc0 .LBB0_516
	s_lshl_b32 s2, s4, 5
	s_cbranch_execz .LBB0_517
	s_branch .LBB0_518

.Lmy_nopf_8:
	s_barrier
.LBB0_609:
	s_cmp_lt_i32 s60, 10
	s_cselect_b64 s[0:1], -1, 0
	s_cmp_gt_i32 s61, 9
	s_cselect_b64 s[2:3], -1, 0
	s_and_b64 s[0:1], s[0:1], s[2:3]
	s_andn2_b64 vcc, exec, s[0:1]
	s_cbranch_vccnz .LBB0_687
	s_cmpk_gt_i32 s10, 0x57f
	v_readfirstlane_b32 s3, v0
	s_cbranch_scc1 .LBB0_626
	v_lshlrev_b32_e32 v2, 4, v0
	v_and_b32_e32 v3, 32, v0
	v_bitop3_b32 v2, v2, v3, 48 bitop3:0x6c
	v_lshrrev_b32_e32 v3, 1, v0
	s_waitcnt vmcnt(0)
	v_lshrrev_b32_e32 v5, 5, v0
	v_and_b32_e32 v3, 24, v3
	v_and_b32_e32 v5, 4, v5
	v_bfe_u32 v6, v0, 2, 2
	v_bfe_u32 v4, v0, 2, 4
	v_or3_b32 v3, v5, v6, v3
	v_lshrrev_b32_e32 v5, 3, v0
	v_and_or_b32 v2, v0, 64, v2
	v_and_or_b32 v6, v5, 48, v4
	v_and_or_b32 v5, v5, 32, v3
	v_lshl_or_b32 v135, v5, 11, v2
	v_bfe_u32 v5, v0, 3, 25
	s_add_u32 s15, s58, 0x1380000
	v_or_b32_e32 v5, 64, v5
	s_movk_i32 s0, 0x70
	s_addc_u32 s17, s59, 0
	v_and_or_b32 v4, v5, s0, v4
	s_movk_i32 s0, 0x60
	s_ashr_i32 s63, s10, 31
	v_and_or_b32 v3, v5, s0, v3
	s_lshr_b32 s0, s63, 29
	s_add_i32 s0, s10, s0
	s_lshr_b32 s6, s3, 6
	s_ashr_i32 s1, s0, 3
	s_and_b32 s0, s0, -8
	s_mov_b32 s86, s62
	s_lshr_b32 s5, s3, 8
	s_lshl_b32 s62, s6, 10
	s_sub_i32 s0, s10, s0
	s_cmp_lt_i32 s0, 0
	s_movk_i32 s64, 0xb1
	s_cselect_b32 s2, s64, 0xb0
	s_mul_i32 s0, s0, s2
	s_add_i32 s0, s0, s1
	s_mul_hi_i32 s1, s0, 0x2e8ba2e9
	s_lshr_b32 s2, s1, 31
	s_ashr_i32 s1, s1, 4
	s_add_i32 s1, s1, s2
	s_lshl_b32 s4, s1, 2
	s_mulk_i32 s1, 0x58
	s_sub_i32 s0, s0, s1
	s_bfe_i32 s1, s0, 0x80000
	s_bfe_u32 s1, s1, 0x2000d
	s_add_i32 s1, s0, s1
	s_bfe_i32 s2, s1, 0x80000
	s_and_b32 s1, s1, 0xfc
	s_sub_i32 s0, s0, s1
	s_sext_i32_i16 s2, s2
	s_sext_i32_i8 s0, s0
	s_lshr_b32 s2, s2, 2
	s_add_i32 s30, s4, s0
	s_ashr_i32 s31, s30, 31
	s_bfe_i64 s[8:9], s[2:3], 0x100000
	s_lshl_b64 s[0:1], s[30:31], 19
	s_lshl_b64 s[8:9], s[8:9], 19
	s_add_u32 s38, s15, s8
	s_addc_u32 s39, s17, s9
	s_add_i32 s31, s62, 0
	v_lshl_or_b32 v134, v6, 11, v2
	v_lshl_or_b32 v136, v4, 11, v2
	v_lshl_or_b32 v137, v3, 11, v2
	s_mov_b64 s[8:9], s[38:39]
	s_add_i32 m0, s31, 0x10000
	v_mov_b32_e32 v2, v135
	v_mov_b32_e32 v3, v137
	global_load_lds_dwordx4 v2, s[8:9]
	s_add_i32 m0, s31, 0x12000
	s_mov_b32 s68, 0
	global_load_lds_dwordx4 v3, s[8:9]
	s_add_u32 s8, s38, 0x40000
	s_addc_u32 s9, s39, 0
	s_add_i32 m0, s31, 0x14000
	s_nop 0
	global_load_lds_dwordx4 v2, s[8:9]
	s_add_i32 m0, s31, 0x16000
	s_add_u32 s42, s16, s0
	s_addc_u32 s43, s79, s1
	global_load_lds_dwordx4 v3, s[8:9]
	s_mov_b64 s[0:1], s[42:43]
	v_mov_b32_e32 v2, v134
	s_mov_b32 m0, s31
	s_add_i32 s65, s31, 0x2000
	v_mov_b32_e32 v3, v136
	global_load_lds_dwordx4 v2, s[0:1]
	s_mov_b32 m0, s65
	s_nop 0
	global_load_lds_dwordx4 v3, s[0:1]
	s_add_u32 s0, s42, 0x40000
	s_addc_u32 s1, s43, 0
	s_add_i32 s66, s31, 0x4000
	s_mov_b32 m0, s66
	s_add_i32 s67, s31, 0x6000
	s_cmp_eq_u32 s5, 1
	global_load_lds_dwordx4 v2, s[0:1]
	s_mov_b32 m0, s67
	s_nop 0
	global_load_lds_dwordx4 v3, s[0:1]
	s_cselect_b64 s[0:1], -1, 0
	s_cmp_lg_u32 s5, 1
	s_cbranch_scc1 .LBB0_613
	s_barrier

.Lmy_nopf_9:
	s_barrier
.LBB0_687:
	s_cmp_lt_i32 s60, 11
	s_cselect_b64 s[0:1], -1, 0
	s_cmp_gt_i32 s61, 10
	s_cselect_b64 s[2:3], -1, 0
	s_and_b64 s[0:1], s[0:1], s[2:3]
	s_andn2_b64 vcc, exec, s[0:1]
	s_cbranch_vccnz .LBB0_788
	s_cmpk_gt_i32 s10, 0xff
	v_readfirstlane_b32 s27, v0
	s_cbranch_scc1 .LBB0_752
	s_ashr_i32 s29, s10, 31
	s_lshr_b32 s0, s29, 29
	s_add_i32 s4, s10, s0
	s_and_b32 s0, s4, -8
	s_sub_i32 s3, s10, s0
	s_cmp_gt_i32 s3, -1
	s_cbranch_scc0 .LBB0_691
	s_lshl_b32 s2, s3, 5
	s_ashr_i32 s0, s4, 3
	s_cbranch_execz .LBB0_692
	s_branch .LBB0_693
